# k42: k41 + attention prologue requests the logf rows before the first K/V tile
# baseline (speedup 1.0000x reference)
; #define LAS __attribute__((address_space(3)))
; #define ATT_GLD16(dst, ptr) asm volatile("global_load_dwordx4 %0, %1, off" : "=&v"(dst) : "v"(ptr) : "memory")
; __device__ __forceinline__ void attn_unit(const UnitDesc& u, LAS unsigned char* shm, float qkmax, float thresh) {
;     ...
;     const bf16_t* ksrc = u.K + (size_t)lane * 512 + wid * 8;
;     const bf16_t* vsrc = u.V + (size_t)(16 * (wid & 3) + (lane >> 2)) * 512 + (wid >> 2) * 32 + (lane & 3) * 8;
;     const float* lsrc = u.LF + (size_t)lane * 8;
;     LAS unsigned char* kdst = shm + LDS_K + wid * 1024 + lane * 16;
;     LAS unsigned char* vdst = shm + LDS_V + wid * 1024 + lane * 16;
;     const int vb0 = (int)(unsigned)(uintptr_t)(shm + LDS_V) + ((lane >> 4) & 1) * 32 + (lane & 3) * 8 + (4 * hi + ((lane & 15) >> 2)) * 64;
;     const LAS unsigned char* kb = shm + LDS_K + hi * 1024 + r32 * 16;
;     ...
;     u32x4 kreg = *(const u32x4*)(ksrc + (size_t)(NT - 1) * 64 * 512), vreg = *(const u32x4*)(vsrc + (size_t)(NT - 1) * 64 * 512);
;     float lfb[4];
; #pragma unroll
;     for (int jb = 0; jb < 4; ++jb) { const int tile = NT - 1 - jb; lfb[jb] = lsrc[(size_t)(tile > 0 ? tile : 0) * 64 * 8]; }
;     u32x4 kA, vA, kB, vB, kC, vC;
;     { const int t2 = NT >= 2 ? NT - 2 : 0, t3 = NT >= 3 ? NT - 3 : 0, t4 = NT >= 4 ? NT - 4 : 0;
;       ATT_GLD16(kA, ksrc + (size_t)t2 * 64 * 512); ATT_GLD16(vA, vsrc + (size_t)t2 * 64 * 512);
;       ATT_GLD16(kB, ksrc + (size_t)t3 * 64 * 512); ATT_GLD16(vB, vsrc + (size_t)t3 * 64 * 512);
;       ATT_GLD16(kC, ksrc + (size_t)t4 * 64 * 512); ATT_GLD16(vC, vsrc + (size_t)t4 * 64 * 512); }
.LBB0_731:
	s_lshl_b64 s[48:49], s[28:29], 2
	v_mov_b32_e32 v12, v208
	s_add_u32 s12, s12, s48
	s_addc_u32 s13, s13, s49
	v_and_b32_e32 v137, 63, v12
	v_readfirstlane_b32 s68, v12
	s_ashr_i32 s52, s68, 6
	v_lshlrev_b32_e32 v0, 10, v137
	v_lshl_add_u64 v[2:3], s[10:11], 0, v[0:1]
	s_lshl_b32 s10, s52, 3
	s_ashr_i32 s11, s10, 31
	v_lshl_add_u64 v[106:107], s[10:11], 1, v[2:3]
	s_lshl_b32 s10, s52, 4
	v_bfe_u32 v0, v12, 2, 4
	v_and_or_b32 v0, s10, 48, v0
	v_lshlrev_b32_e32 v0, 10, v0
	s_add_i32 s28, s53, s66
	v_lshl_add_u64 v[2:3], s[8:9], 0, v[0:1]
	s_ashr_i32 s8, s68, 3
	s_ashr_i32 s67, s28, 6
	s_andn2_b32 s8, s8, 31
	v_lshlrev_b32_e32 v138, 3, v12
	s_ashr_i32 s9, s8, 31
	v_and_b32_e32 v13, 24, v138
	s_add_i32 s48, s67, -1
	v_lshl_add_u64 v[2:3], s[8:9], 1, v[2:3]
	v_lshlrev_b32_e32 v0, 1, v13
	s_ashr_i32 s49, s48, 31
	v_lshl_add_u64 v[108:109], v[2:3], 0, v[0:1]
	v_lshlrev_b32_e32 v0, 5, v137
	s_lshl_b64 s[8:9], s[48:49], 16
	s_max_i32 s28, s48, 0
	v_lshl_add_u64 v[110:111], s[12:13], 0, v[0:1]
	v_lshl_add_u64 v[2:3], v[106:107], 0, s[8:9]
	v_lshl_add_u64 v[6:7], v[108:109], 0, s[8:9]
	s_lshl_b64 s[8:9], s[28:29], 11
	v_lshl_add_u64 v[10:11], v[110:111], 0, s[8:9]
	s_max_i32 s8, s67, 2
	s_add_i32 s28, s8, -2
	s_lshl_b64 s[8:9], s[28:29], 11
	v_lshl_add_u64 v[16:17], v[110:111], 0, s[8:9]
	s_max_i32 s8, s67, 3
	s_add_i32 s8, s8, -3
	s_mov_b32 s9, s29
	s_lshl_b64 s[10:11], s[8:9], 11
	v_lshl_add_u64 v[18:19], v[110:111], 0, s[10:11]
	s_max_i32 s10, s67, 4
	s_add_i32 s10, s10, -4
	s_mov_b32 s11, s29
	s_lshl_b64 s[12:13], s[10:11], 11
	v_lshl_add_u64 v[20:21], v[110:111], 0, s[12:13]
	global_load_dword v14, v[10:11], off
	global_load_dword v140, v[16:17], off
	global_load_dword v141, v[18:19], off
	global_load_dword v139, v[20:21], off
	global_load_dwordx4 v[2:5], v[2:3], off
	global_load_dwordx4 v[6:9], v[6:7], off
	s_lshl_b32 s49, s52, 5
	s_cmp_lt_i32 s49, s53
	s_cselect_b64 s[58:59], -1, 0
	s_cmp_ge_i32 s49, s53
	s_cselect_b64 s[60:61], -1, 0
	v_and_b32_e32 v135, 31, v12
	v_bfe_u32 v136, v12, 5, 1
	s_and_b64 vcc, exec, s[60:61]
	v_or_b32_e32 v10, s49, v135
	s_cbranch_vccnz .LBB0_733
	v_ashrrev_i32_e32 v11, 31, v10
	v_lshlrev_b64 v[16:17], 10, v[10:11]
	v_lshl_add_u64 v[16:17], s[6:7], 0, v[16:17]
	v_lshlrev_b32_e32 v0, 4, v136
	v_lshl_add_u64 v[16:17], v[16:17], 0, v[0:1]
	global_load_dwordx4 v[94:97], v[16:17], off
	global_load_dwordx4 v[98:101], v[16:17], off offset:32
	global_load_dwordx4 v[102:105], v[16:17], off offset:64
	global_load_dwordx4 v[90:93], v[16:17], off offset:96
	s_branch .LBB0_734

; #define DPP_SHL(v, n) __builtin_bit_cast(float, __builtin_amdgcn_update_dpp(0, __builtin_bit_cast(int, (v)), 0x100 | (n), 0xF, 0xF, true))
; __device__ __forceinline__ float lane0(float v) { return __builtin_bit_cast(float, __builtin_amdgcn_readfirstlane(__builtin_bit_cast(int, v))); }
; #define ATT_GLD16(dst, ptr) asm volatile("global_load_dwordx4 %0, %1, off" : "=&v"(dst) : "v"(ptr) : "memory")
; __device__ __forceinline__ float suffix_incl(float v, int lane) {
;     v += DPP_SHL(v, 1); v += DPP_SHL(v, 2); v += DPP_SHL(v, 4); v += DPP_SHL(v, 8);
;     const float t1 = __builtin_bit_cast(float, __builtin_amdgcn_readlane(__builtin_bit_cast(int, v), 16)), t2 = __builtin_bit_cast(float, __builtin_amdgcn_readlane(__builtin_bit_cast(int, v), 32)),
;                 t3 = __builtin_bit_cast(float, __builtin_amdgcn_readlane(__builtin_bit_cast(int, v), 48));
;     const int row = lane >> 4;
;     const float add = (row == 0) ? (t1 + t2) + t3 : (row == 1) ? t2 + t3 : (row == 2) ? t3 : 0.f;
;     return v + add;
; }
; __device__ __forceinline__ void attn_unit(const UnitDesc& u, LAS unsigned char* shm, float qkmax, float thresh) {
;     ...
;     { const int t2 = NT >= 2 ? NT - 2 : 0, t3 = NT >= 3 ? NT - 3 : 0, t4 = NT >= 4 ? NT - 4 : 0;
;       ATT_GLD16(kA, ksrc + (size_t)t2 * 64 * 512); ATT_GLD16(vA, vsrc + (size_t)t2 * 64 * 512);
;       ATT_GLD16(kB, ksrc + (size_t)t3 * 64 * 512); ATT_GLD16(vB, vsrc + (size_t)t3 * 64 * 512);
;       ATT_GLD16(kC, ksrc + (size_t)t4 * 64 * 512); ATT_GLD16(vC, vsrc + (size_t)t4 * 64 * 512); }
;     bf16x8 qr[4];
; #pragma unroll
;     for (int d0 = 0; d0 < 4; ++d0) qr[d0] = (bf16x8){0, 0, 0, 0, 0, 0, 0, 0};
;     if (active) { const bf16_t* Qw = u.Q + (size_t)(wid * 32 + r32) * 512;
; #pragma unroll
;         for (int d0 = 0; d0 < 4; ++d0) qr[d0] = *(const bf16x8*)(Qw + d0 * 16 + hi * 8); }
;     float carry = 0.f, Rown = 0.f, Rq0 = 0.f, inc4[4];
; #pragma unroll
;     for (int i = 0; i < 4; ++i) inc4[i] = suffix_incl(lfb[i], lane);
; #pragma unroll
;     for (int i = 0; i < 4; ++i) { if (i < nband) { const int jb = nband - 1 - i; const float R = carry + inc4[i] - lfb[i];
;         const float ro = __shfl(R, 32 * (wid & 1) + r32); if (jb == (wid >> 1)) Rown = ro;
;         if (jb == 0) Rq0 = __shfl(R, 0);
;         carry += lane0(inc4[i]); } }
.LBB0_734:
	s_lshl_b64 s[12:13], s[28:29], 16
	v_lshl_add_u64 v[188:189], v[106:107], 0, s[12:13]
	global_load_dwordx4 v[66:69], v[188:189], off
	v_lshl_add_u64 v[188:189], v[108:109], 0, s[12:13]
	global_load_dwordx4 v[74:77], v[188:189], off
	s_lshl_b64 s[8:9], s[8:9], 16
	v_lshl_add_u64 v[188:189], v[106:107], 0, s[8:9]
	global_load_dwordx4 v[70:73], v[188:189], off
	v_lshl_add_u64 v[188:189], v[108:109], 0, s[8:9]
	global_load_dwordx4 v[82:85], v[188:189], off
	s_lshl_b64 s[8:9], s[10:11], 16
	v_lshl_add_u64 v[188:189], v[106:107], 0, s[8:9]
	global_load_dwordx4 v[78:81], v[188:189], off
	v_lshl_add_u64 v[188:189], v[108:109], 0, s[8:9]
	global_load_dwordx4 v[86:89], v[188:189], off
	v_lshrrev_b32_e32 v0, 4, v137
	v_cmp_ne_u32_e64 s[8:9], 1, v0
	v_cmp_eq_u32_e64 s[10:11], 2, v0
	s_waitcnt vmcnt(15)
	v_add_f32_dpp v0, v14, v14 row_shl:1 row_mask:0xf bank_mask:0xf bound_ctrl:1
	v_cmp_lt_u32_e64 s[6:7], 15, v137
	s_nop 0
	v_add_f32_dpp v0, v0, v0 row_shl:2 row_mask:0xf bank_mask:0xf bound_ctrl:1
	s_nop 1
	v_add_f32_dpp v0, v0, v0 row_shl:4 row_mask:0xf bank_mask:0xf bound_ctrl:1
	s_nop 1
	v_add_f32_dpp v0, v0, v0 row_shl:8 row_mask:0xf bank_mask:0xf bound_ctrl:1
	s_nop 0
	v_readlane_b32 s28, v0, 16
	v_readlane_b32 s70, v0, 32
	v_readlane_b32 s69, v0, 48
	s_and_saveexec_b64 s[12:13], s[6:7]
	s_xor_b64 s[12:13], exec, s[12:13]
	s_cbranch_execz .LBB0_740
	s_and_saveexec_b64 s[64:65], s[8:9]
	s_xor_b64 s[64:65], exec, s[64:65]
	v_mov_b32_e32 v11, s69
	v_cndmask_b32_e64 v11, 0, v11, s[10:11]
	s_andn2_saveexec_b64 s[64:65], s[64:65]
	v_mov_b32_e32 v11, s69
	v_add_f32_e32 v11, s70, v11
	s_or_b64 exec, exec, s[64:65]
.LBB0_740:
	s_andn2_saveexec_b64 s[12:13], s[12:13]
	v_mov_b32_e32 v11, s70
	v_add_f32_e32 v11, s28, v11
	v_add_f32_e32 v11, s69, v11
	s_or_b64 exec, exec, s[12:13]
	s_waitcnt vmcnt(14)
	v_add_f32_dpp v15, v140, v140 row_shl:1 row_mask:0xf bank_mask:0xf bound_ctrl:1
	s_nop 1
	v_add_f32_dpp v15, v15, v15 row_shl:2 row_mask:0xf bank_mask:0xf bound_ctrl:1
	s_nop 1
	v_add_f32_dpp v15, v15, v15 row_shl:4 row_mask:0xf bank_mask:0xf bound_ctrl:1
	s_nop 1
	v_add_f32_dpp v15, v15, v15 row_shl:8 row_mask:0xf bank_mask:0xf bound_ctrl:1
	s_nop 0
	v_readlane_b32 s28, v15, 16
	v_readlane_b32 s70, v15, 32
	v_readlane_b32 s69, v15, 48
	s_and_saveexec_b64 s[12:13], s[6:7]
	s_xor_b64 s[12:13], exec, s[12:13]
	s_cbranch_execz .LBB0_748
	s_and_saveexec_b64 s[64:65], s[8:9]
	s_xor_b64 s[64:65], exec, s[64:65]
	v_mov_b32_e32 v16, s69
	v_cndmask_b32_e64 v16, 0, v16, s[10:11]
	s_andn2_saveexec_b64 s[64:65], s[64:65]
	v_mov_b32_e32 v16, s69
	v_add_f32_e32 v16, s70, v16
	s_or_b64 exec, exec, s[64:65]
.LBB0_748:
	s_andn2_saveexec_b64 s[12:13], s[12:13]
	v_mov_b32_e32 v16, s70
	v_add_f32_e32 v16, s28, v16
	v_add_f32_e32 v16, s69, v16
	s_or_b64 exec, exec, s[12:13]
	s_waitcnt vmcnt(13)
	v_add_f32_dpp v17, v141, v141 row_shl:1 row_mask:0xf bank_mask:0xf bound_ctrl:1
	s_nop 1
	v_add_f32_dpp v17, v17, v17 row_shl:2 row_mask:0xf bank_mask:0xf bound_ctrl:1
	s_nop 1
	v_add_f32_dpp v17, v17, v17 row_shl:4 row_mask:0xf bank_mask:0xf bound_ctrl:1
	s_nop 1
	v_add_f32_dpp v17, v17, v17 row_shl:8 row_mask:0xf bank_mask:0xf bound_ctrl:1
	s_nop 0
	v_readlane_b32 s28, v17, 16
	v_readlane_b32 s70, v17, 32
	v_readlane_b32 s69, v17, 48
	s_and_saveexec_b64 s[12:13], s[6:7]
	s_xor_b64 s[12:13], exec, s[12:13]
	s_cbranch_execz .LBB0_756
	s_and_saveexec_b64 s[64:65], s[8:9]
	s_xor_b64 s[64:65], exec, s[64:65]
	v_mov_b32_e32 v18, s69
	v_cndmask_b32_e64 v18, 0, v18, s[10:11]
	s_andn2_saveexec_b64 s[64:65], s[64:65]
	v_mov_b32_e32 v18, s69
	v_add_f32_e32 v18, s70, v18
	s_or_b64 exec, exec, s[64:65]
.LBB0_756:
	s_andn2_saveexec_b64 s[12:13], s[12:13]
	v_mov_b32_e32 v18, s70
	v_add_f32_e32 v18, s28, v18
	v_add_f32_e32 v18, s69, v18
	s_or_b64 exec, exec, s[12:13]
	s_waitcnt vmcnt(12)
	v_add_f32_dpp v19, v139, v139 row_shl:1 row_mask:0xf bank_mask:0xf bound_ctrl:1
	s_nop 1
	v_add_f32_dpp v19, v19, v19 row_shl:2 row_mask:0xf bank_mask:0xf bound_ctrl:1
	s_nop 1
	v_add_f32_dpp v19, v19, v19 row_shl:4 row_mask:0xf bank_mask:0xf bound_ctrl:1
	s_nop 1
	v_add_f32_dpp v19, v19, v19 row_shl:8 row_mask:0xf bank_mask:0xf bound_ctrl:1
	s_nop 0
	v_readlane_b32 s28, v19, 16
	v_readlane_b32 s70, v19, 32
	v_readlane_b32 s69, v19, 48
	s_and_saveexec_b64 s[12:13], s[6:7]
	s_xor_b64 s[12:13], exec, s[12:13]
	s_cbranch_execz .LBB0_764
	s_and_saveexec_b64 s[64:65], s[8:9]
	s_xor_b64 s[64:65], exec, s[64:65]
	v_mov_b32_e32 v20, s69
	v_cndmask_b32_e64 v20, 0, v20, s[10:11]
	s_andn2_saveexec_b64 s[64:65], s[64:65]
	v_mov_b32_e32 v20, s69
	v_add_f32_e32 v20, s70, v20
	s_or_b64 exec, exec, s[64:65]

; #define LAS __attribute__((address_space(3)))
; __device__ __forceinline__ float lane0(float v) { return __builtin_bit_cast(float, __builtin_amdgcn_readfirstlane(__builtin_bit_cast(int, v))); }
; __device__ __forceinline__ void attn_unit(const UnitDesc& u, LAS unsigned char* shm, float qkmax, float thresh) {
;     ...
;     const float ci = -Rown * LOG2E - qkmax;
;     const float kbq0 = Rq0 * LOG2E;
;     const int qabs = u.q0 + wid * 32 + r32;
;     float l_reg = 0.f; f32x16 o[2]; o[0] = f32x16{}; o[1] = f32x16{};
;     float lA = lfb[1], lB = lfb[2], lC = lfb[3];
;     { const float lf = lfb[0]; const float inc = inc4[0]; wsf[lane] = (inc - lf) * LOG2E; carry = lane0(inc);
;       *(LAS u32x4*)kdst = kreg; *(LAS u32x4*)vdst = vreg;
;       asm volatile("" : "+v"(qr[0]), "+v"(qr[1]), "+v"(qr[2]), "+v"(qr[3]));
;       asm volatile("s_waitcnt vmcnt(0)" : "+v"(kA), "+v"(vA), "+v"(kB), "+v"(vB), "+v"(kC), "+v"(vC) :: "memory"); }
;     int slot = 0, tile = NT - 1; bool stop = false;
.LBB0_772:
	v_lshlrev_b32_e32 v15, 1, v12
	s_lshl_b32 s12, s52, 10
	v_and_b32_e32 v15, 32, v15
	s_add_i32 s13, 0, 0x2000
	v_lshlrev_b32_e32 v142, 2, v136
	v_lshrrev_b32_e32 v12, 2, v12
	s_add_i32 s12, s12, 0
	v_add_u32_e32 v15, s13, v15
	v_and_or_b32 v12, v12, 3, v142
	s_lshl_b32 s13, s52, 9
	v_lshlrev_b32_e32 v12, 6, v12
	s_sub_i32 s53, s12, s13
	v_add_u32_e32 v147, s66, v10
	v_sub_f32_e32 v10, v0, v14
	v_lshl_add_u32 v143, v137, 4, s12
	v_add3_u32 v144, v15, v13, v12
	s_mov_b32 s12, 0xbfb8aa3b
	s_waitcnt lgkmcnt(0)
	v_mul_f32_e32 v146, 0x3fb8aa3b, v11
	v_mul_f32_e32 v10, 0x3fb8aa3b, v10
	v_lshl_add_u32 v11, v137, 2, s53
	v_mov_b32_e32 v14, v1
	v_mov_b32_e32 v15, v1
	v_lshlrev_b32_e32 v16, 10, v136
	v_lshlrev_b32_e32 v17, 4, v135
	v_fma_f32 v112, v21, s12, -v130
	v_mul_f32_e32 v197, 0x3fb8aa3b, v21
	s_mov_b64 s[98:99], 0
	s_nop 0
	v_readfirstlane_b32 s100, v197
	s_nop 3
	v_mov_b32_e32 v197, s100
	ds_write_b32 v11, v10 offset:32768
	v_readfirstlane_b32 s12, v0
	s_waitcnt vmcnt(10)
	ds_write_b128 v143, v[2:5]
	ds_write_b128 v143, v[6:9] offset:8192
	v_mov_b32_e32 v0, v1
	v_mov_b32_e32 v2, v1
	v_mov_b32_e32 v3, v1
	v_mov_b32_e32 v4, v1
	v_mov_b32_e32 v5, v1
	v_mov_b32_e32 v6, v1
	v_mov_b32_e32 v7, v1
	v_mov_b32_e32 v8, v1
	v_mov_b32_e32 v9, v1
	v_mov_b32_e32 v10, v1
	v_mov_b32_e32 v11, v1
	v_mov_b32_e32 v12, v1
	v_mov_b32_e32 v13, v1
	v_mov_b64_e32 v[48:49], v[14:15]
	v_mov_b64_e32 v[64:65], v[14:15]
	v_mov_b64_e32 v[32:33], v[14:15]
	v_add3_u32 v145, 0, v16, v17
	s_add_i32 s73, s66, s49
	v_mov_b64_e32 v[46:47], v[12:13]
	v_mov_b64_e32 v[44:45], v[10:11]
	v_mov_b64_e32 v[42:43], v[8:9]
	v_mov_b64_e32 v[40:41], v[6:7]
	v_mov_b64_e32 v[38:39], v[4:5]
	v_mov_b64_e32 v[36:37], v[2:3]
	v_mov_b64_e32 v[34:35], v[0:1]
	v_mov_b64_e32 v[62:63], v[12:13]
	v_mov_b64_e32 v[60:61], v[10:11]
	v_mov_b64_e32 v[58:59], v[8:9]
	v_mov_b64_e32 v[56:57], v[6:7]
	v_mov_b64_e32 v[54:55], v[4:5]
	v_mov_b64_e32 v[52:53], v[2:3]
	v_mov_b64_e32 v[50:51], v[0:1]
	v_mov_b64_e32 v[30:31], v[12:13]
	v_mov_b64_e32 v[28:29], v[10:11]
	v_mov_b64_e32 v[26:27], v[8:9]
	v_mov_b64_e32 v[24:25], v[6:7]
	v_mov_b64_e32 v[22:23], v[4:5]
	v_mov_b64_e32 v[20:21], v[2:3]
	v_mov_b64_e32 v[18:19], v[0:1]
	v_mov_b64_e32 v[16:17], v[14:15]
	s_sub_i32 s72, s67, s28
	s_add_i32 s73, s73, 31
	v_mov_b32_e32 v113, v112
	v_mov_b32_e32 v114, v112
	v_mov_b32_e32 v115, v112
	v_mov_b32_e32 v116, v112
	v_mov_b32_e32 v117, v112
	v_mov_b32_e32 v118, v112
	v_mov_b32_e32 v119, v112
	v_mov_b32_e32 v120, v112
	v_mov_b32_e32 v121, v112
	v_mov_b32_e32 v122, v112
	v_mov_b32_e32 v123, v112
	v_mov_b32_e32 v124, v112
	v_mov_b32_e32 v125, v112
	v_mov_b32_e32 v126, v112
	v_mov_b32_e32 v127, v112
	s_lshl_b32 s75, s67, 6
	s_mov_b32 s70, 0
	v_mov_b32_e32 v148, 0
	s_mov_b64 s[62:63], 0
	v_mov_b32_e32 v150, s12
	v_mov_b64_e32 v[14:15], v[12:13]
	v_mov_b64_e32 v[12:13], v[10:11]
	v_mov_b64_e32 v[10:11], v[8:9]
	v_mov_b64_e32 v[8:9], v[6:7]
	v_mov_b64_e32 v[6:7], v[4:5]
	v_mov_b64_e32 v[4:5], v[2:3]
	v_mov_b64_e32 v[2:3], v[0:1]
	s_waitcnt vmcnt(6)
	s_branch .LBB0_777
